# v26 plus DPP row ops (quad_perm, row_half_mirror, row_mirror) instead of ds_bpermute round trips for four of five butterfly hops in the MLA post pass reductions
# baseline (speedup 1.0000x reference)
.LBB0_260:
	s_or_b64 exec, exec, s[18:19]
	v_lshl_add_u64 v[22:23], s[26:27], 0, v[16:17]
	v_add_co_u32_e32 v24, vcc, 0xf8ac000, v22
	s_nop 1
	v_addc_co_u32_e32 v25, vcc, 0, v23, vcc
	s_waitcnt lgkmcnt(0)
	global_load_ushort v0, v[24:25], off offset:256
	global_load_ushort v22, v[24:25], off offset:384
	global_load_ushort v61, v[24:25], off offset:512
	global_load_ushort v62, v[24:25], off offset:640
	global_load_ushort v63, v[24:25], off offset:768
	global_load_ushort v64, v[24:25], off offset:896
	v_lshl_add_u64 v[66:67], s[26:27], 0, v[18:19]
	global_load_ushort v60, v[66:67], off
	s_waitcnt vmcnt(5)
	v_lshlrev_b32_e32 v0, 16, v0
	v_lshlrev_b32_e32 v46, 16, v22
	v_mul_f32_e32 v47, v46, v46
	v_fmac_f32_e32 v47, v0, v0
	s_waitcnt vmcnt(3)
	v_lshlrev_b32_e32 v28, 16, v61
	v_lshlrev_b32_e32 v29, 16, v62
	v_pk_mul_f32 v[30:31], v[28:29], v[28:29]
	s_waitcnt vmcnt(1)
	v_lshlrev_b32_e32 v26, 16, v63
	v_lshlrev_b32_e32 v27, 16, v64
	global_load_ushort v22, v[24:25], off offset:1024
	global_load_ushort v23, v[24:25], off offset:1152
	global_load_ushort v44, v[24:25], off offset:1280
	s_nop 0
	global_load_ushort v24, v[24:25], off offset:1408
	v_add_f32_e32 v30, v47, v30
	v_pk_mul_f32 v[40:41], v[26:27], v[26:27]
	v_add_f32_e32 v30, v30, v31
	v_add_f32_e32 v30, v30, v40
	v_add_f32_e32 v30, v30, v41
	s_nop 1
	v_add_f32_dpp v30, v30, v30 quad_perm:[1,0,3,2] row_mask:0xf bank_mask:0xf
	s_nop 1
	v_add_f32_dpp v30, v30, v30 quad_perm:[2,3,0,1] row_mask:0xf bank_mask:0xf
	s_nop 1
	v_add_f32_dpp v30, v30, v30 row_half_mirror row_mask:0xf bank_mask:0xf
	s_nop 1
	v_add_f32_dpp v30, v30, v30 row_mirror row_mask:0xf bank_mask:0xf
	ds_bpermute_b32 v31, v36, v30
	s_waitcnt lgkmcnt(0)
	v_add_f32_e32 v31, v30, v31
	v_mov_b32_e32 v41, v31
	v_nop
	v_nop
	v_permlane32_swap_b32 v31, v41
	s_waitcnt vmcnt(3)
	v_lshlrev_b32_e32 v22, 16, v22
	s_waitcnt vmcnt(2)
	v_lshlrev_b32_e32 v23, 16, v23
	v_pk_mul_f32 v[42:43], v[22:23], v[22:23]
	s_waitcnt vmcnt(0)
	v_lshlrev_b32_e32 v25, 16, v24
	v_lshlrev_b32_e32 v24, 16, v44
	v_pk_mul_f32 v[44:45], v[24:25], v[24:25]
	v_add_f32_e32 v42, v42, v43
	v_add_f32_e32 v42, v42, v44
	v_add_f32_e32 v42, v42, v45
	v_mov_b32_e32 v30, v42
	s_nop 1
	v_add_f32_dpp v30, v30, v30 quad_perm:[1,0,3,2] row_mask:0xf bank_mask:0xf
	s_nop 1
	v_add_f32_dpp v30, v30, v30 quad_perm:[2,3,0,1] row_mask:0xf bank_mask:0xf
	s_nop 1
	v_add_f32_dpp v30, v30, v30 row_half_mirror row_mask:0xf bank_mask:0xf
	s_nop 1
	v_add_f32_dpp v30, v30, v30 row_mirror row_mask:0xf bank_mask:0xf
	ds_bpermute_b32 v40, v36, v30
	s_waitcnt lgkmcnt(0)
	v_add_f32_e32 v30, v30, v40
	v_mov_b32_e32 v40, v30
	v_nop
	v_nop
	v_permlane32_swap_b32 v30, v40
	v_mov_b32_e32 v43, v50
	v_pk_add_f32 v[30:31], v[30:31], v[40:41]
	s_nop 0
	v_pk_fma_f32 v[30:31], v[30:31], s[40:41], v[252:253] op_sel_hi:[1,1,0]
	s_nop 0
	v_mul_f32_e32 v40, 0x4b800000, v31
	v_cmp_gt_f32_e64 s[18:19], s67, v31
	v_cmp_gt_f32_e32 vcc, s67, v30
	s_nop 0
	v_cndmask_b32_e64 v31, v31, v40, s[18:19]
	v_rsq_f32_e32 v31, v31
	s_nop 0
	v_mul_f32_e32 v40, 0x45800000, v31
	v_cndmask_b32_e64 v40, v31, v40, s[18:19]
	v_mul_f32_e32 v0, v40, v0
	v_mul_f32_e32 v31, 0x4b800000, v30
	v_cndmask_b32_e32 v30, v30, v31, vcc
	v_rsq_f32_e32 v41, v30
	v_lshl_add_u64 v[30:31], s[26:27], 0, v[14:15]
	s_mov_b32 s18, 0xecac000
	v_add_co_u32_e64 v30, s[18:19], s18, v30
	v_mul_f32_e32 v42, 0x45800000, v41
	s_nop 0
	v_addc_co_u32_e64 v31, s[18:19], 0, v31, s[18:19]
	v_mul_f32_e32 v0, v43, v0
	v_bfe_u32 v43, v0, 16, 1
	v_add3_u32 v0, v0, v43, s44
	v_mov_b32_e32 v43, v51
	s_nop 0
	global_store_short_d16_hi v[30:31], v0, off offset:256
	v_mul_f32_e32 v0, v40, v46
	v_mul_f32_e32 v0, v43, v0
	v_bfe_u32 v43, v0, 16, 1
	v_add3_u32 v0, v0, v43, s44
	global_store_short_d16_hi v[30:31], v0, off offset:384
	v_mul_f32_e32 v0, v40, v28
	v_mov_b32_e32 v28, v52
	v_mul_f32_e32 v0, v0, v28
	v_bfe_u32 v28, v0, 16, 1
	v_add3_u32 v0, v0, v28, s44
	v_mov_b32_e32 v28, v53
	s_nop 0
	global_store_short_d16_hi v[30:31], v0, off offset:512
	v_mul_f32_e32 v0, v40, v29
	v_mul_f32_e32 v0, v0, v28
	v_bfe_u32 v28, v0, 16, 1
	v_add3_u32 v0, v0, v28, s44
	global_store_short_d16_hi v[30:31], v0, off offset:640
	v_mul_f32_e32 v0, v40, v26
	v_mov_b32_e32 v26, v54
	v_mul_f32_e32 v0, v0, v26
	v_bfe_u32 v26, v0, 16, 1
	v_add3_u32 v0, v0, v26, s44
	v_mov_b32_e32 v26, v55
	s_nop 0
	global_store_short_d16_hi v[30:31], v0, off offset:768
	v_mul_f32_e32 v0, v40, v27
	v_cndmask_b32_e32 v40, v41, v42, vcc
	v_mov_b32_e32 v41, v56
	v_mul_f32_e32 v22, v40, v22
	v_mul_f32_e32 v0, v0, v26
	v_bfe_u32 v26, v0, 16, 1
	v_add3_u32 v0, v0, v26, s44
	global_store_short_d16_hi v[30:31], v0, off offset:896
	v_lshlrev_b64 v[26:27], 9, v[20:21]
	v_ashrrev_i32_e32 v0, 7, v2
	v_lshl_add_u64 v[28:29], v[6:7], 0, v[26:27]
	v_and_or_b32 v26, v0, -2, v5
	v_ashrrev_i32_e32 v27, 31, v26
	v_and_b32_e32 v0, 0xff00, v39
	v_lshlrev_b64 v[30:31], 18, v[26:27]
	v_lshl_add_u64 v[30:31], s[2:3], 0, v[30:31]
	v_lshlrev_b32_e32 v0, 2, v0
	v_mul_f32_e32 v22, v22, v41
	v_lshl_add_u64 v[30:31], v[30:31], 0, v[0:1]
	v_lshlrev_b32_e32 v0, 2, v4
	v_bfe_u32 v41, v22, 16, 1
	v_lshl_add_u64 v[30:31], v[30:31], 0, v[0:1]
	v_add3_u32 v41, v22, v41, s44
	global_store_short_d16_hi v[28:29], v41, off
	s_and_saveexec_b64 s[18:19], s[14:15]
	s_cbranch_execz .LBB0_262
	global_store_dword v[30:31], v22, off
